# v25 + nt hint on the adaLN modulation GEMV's one-shot f32 weight loads (400 MB)
# speedup vs baseline: 1.0252x; 1.0046x over previous
.LBB0_101:
	v_lshl_add_u64 v[16:17], v[6:7], 0, s[6:7]
	v_add_co_u32_e64 v72, s[4:5], s19, v16
	global_load_dwordx3 v[68:70], v[16:17], off nt
	s_nop 0
	v_addc_co_u32_e64 v73, s[4:5], 0, v17, s[4:5]
	v_add_co_u32_e64 v76, s[4:5], s21, v16
	v_mov_b32_e32 v23, s9
	s_nop 0
	v_addc_co_u32_e64 v77, s[4:5], 0, v17, s[4:5]
	v_add_co_u32_e64 v80, s[4:5], s22, v16
	ds_read_b128 v[24:27], v23
	ds_read_b128 v[28:31], v23 offset:16
	ds_read_b128 v[32:35], v23 offset:32
	ds_read_b128 v[0:3], v23 offset:48
	v_addc_co_u32_e64 v81, s[4:5], 0, v17, s[4:5]
	v_add_co_u32_e64 v84, s[4:5], s23, v16
	ds_read_b128 v[36:39], v23 offset:8192
	ds_read_b128 v[40:43], v23 offset:8208
	ds_read_b128 v[44:47], v23 offset:16384
	ds_read_b128 v[48:51], v23 offset:16400
	v_addc_co_u32_e64 v85, s[4:5], 0, v17, s[4:5]
	v_add_co_u32_e64 v88, s[4:5], s24, v16
	ds_read_b128 v[52:55], v23 offset:8224
	ds_read_b128 v[56:59], v23 offset:8240
	v_addc_co_u32_e64 v89, s[4:5], 0, v17, s[4:5]
	v_add_co_u32_e64 v92, s[4:5], s25, v16
	ds_read_b128 v[60:63], v23 offset:16416
	ds_read_b128 v[64:67], v23 offset:16432
	v_addc_co_u32_e64 v93, s[4:5], 0, v17, s[4:5]
	v_add_co_u32_e64 v96, s[4:5], s26, v16
	s_waitcnt lgkmcnt(11)
	v_mov_b32_e32 v132, v25
	v_addc_co_u32_e64 v97, s[4:5], 0, v17, s[4:5]
	v_add_co_u32_e64 v100, s[4:5], s27, v16
	s_waitcnt lgkmcnt(7)
	v_mov_b32_e32 v133, v37
	v_addc_co_u32_e64 v101, s[4:5], 0, v17, s[4:5]
	v_add_co_u32_e64 v104, s[4:5], s28, v16
	v_mov_b32_e32 v134, v26
	s_nop 0
	v_addc_co_u32_e64 v105, s[4:5], 0, v17, s[4:5]
	v_add_co_u32_e64 v108, s[4:5], s29, v16
	v_mov_b32_e32 v135, v38
	s_nop 0
	v_addc_co_u32_e64 v109, s[4:5], 0, v17, s[4:5]
	v_add_co_u32_e64 v112, s[4:5], s30, v16
	v_mov_b32_e32 v138, v27
	s_nop 0
	v_addc_co_u32_e64 v113, s[4:5], 0, v17, s[4:5]
	v_add_co_u32_e64 v116, s[4:5], s31, v16
	s_waitcnt lgkmcnt(5)
	v_mov_b32_e32 v136, v47
	v_addc_co_u32_e64 v117, s[4:5], 0, v17, s[4:5]
	v_add_co_u32_e64 v120, s[4:5], s34, v16
	v_mov_b32_e32 v140, v39
	s_nop 0
	v_addc_co_u32_e64 v121, s[4:5], 0, v17, s[4:5]
	v_add_co_u32_e64 v124, s[4:5], s35, v16
	v_mov_b32_e32 v142, v28
	s_nop 0
	v_addc_co_u32_e64 v125, s[4:5], 0, v17, s[4:5]
	v_add_co_u32_e64 v16, s[4:5], s36, v16
	v_mov_b32_e32 v143, v40
	s_nop 0
	v_addc_co_u32_e64 v17, s[4:5], 0, v17, s[4:5]
	global_load_dwordx3 v[72:74], v[72:73], off nt
	s_nop 0
	global_load_dwordx3 v[76:78], v[76:77], off nt
	s_nop 0
	global_load_dwordx3 v[80:82], v[80:81], off nt
	s_nop 0
	global_load_dwordx3 v[84:86], v[84:85], off nt
	s_nop 0
	global_load_dwordx3 v[88:90], v[88:89], off nt
	s_nop 0
	global_load_dwordx3 v[92:94], v[92:93], off nt
	s_nop 0
	global_load_dwordx3 v[96:98], v[96:97], off nt
	s_nop 0
	global_load_dwordx3 v[100:102], v[100:101], off nt
	s_nop 0
	global_load_dwordx3 v[104:106], v[104:105], off nt
	s_nop 0
	global_load_dwordx3 v[108:110], v[108:109], off nt
	s_nop 0
	global_load_dwordx3 v[112:114], v[112:113], off nt
	s_nop 0
	global_load_dwordx3 v[116:118], v[116:117], off nt
	s_nop 0
	global_load_dwordx3 v[120:122], v[120:121], off nt
	s_nop 0
	global_load_dwordx3 v[124:126], v[124:125], off nt
	s_nop 0
	global_load_dwordx3 v[128:130], v[16:17], off nt
	v_mov_b32_e32 v16, v24
	v_mov_b32_e32 v17, v36
	v_mov_b32_e32 v144, v29
	v_mov_b32_e32 v145, v41
	v_mov_b32_e32 v146, v30
	v_mov_b32_e32 v147, v42
	s_waitcnt vmcnt(15)
	v_pk_fma_f32 v[12:13], v[68:69], v[24:25], v[12:13] op_sel_hi:[1,0,1]
	v_pk_mov_b32 v[178:179], v[68:69], v[68:69] op_sel:[1,0]
	v_mov_b32_e32 v180, v70
	v_pk_fma_f32 v[14:15], v[68:69], v[44:45], v[14:15] op_sel_hi:[1,0,1]
	v_fmac_f32_e32 v22, v70, v44
	v_mov_b32_e32 v181, v179
	v_mov_b32_e32 v179, v70
	v_pk_fma_f32 v[10:11], v[180:181], v[16:17], v[10:11]
	v_pk_fma_f32 v[8:9], v[178:179], v[36:37], v[8:9] op_sel_hi:[1,0,1]
	v_mov_b32_e32 v148, v31
	v_mov_b32_e32 v150, v43
	s_waitcnt lgkmcnt(4)
	v_mov_b32_e32 v152, v51
	v_mov_b32_e32 v154, v32
	s_waitcnt lgkmcnt(3)
	v_mov_b32_e32 v155, v52
	v_mov_b32_e32 v156, v33
	v_mov_b32_e32 v157, v53
	v_mov_b32_e32 v158, v34
	v_mov_b32_e32 v159, v54
	v_mov_b32_e32 v160, v35
	v_mov_b32_e32 v162, v55
	s_waitcnt lgkmcnt(1)
	v_mov_b32_e32 v164, v63
	v_mov_b32_e32 v166, v0
	v_mov_b32_e32 v167, v56
	v_mov_b32_e32 v168, v1
	v_mov_b32_e32 v169, v57
	s_add_u32 s6, s6, 0xc0000
	v_mov_b32_e32 v170, v2
	v_mov_b32_e32 v171, v58
	v_mov_b32_e32 v172, v3
	s_addc_u32 s7, s7, 0
	s_add_i32 s9, s9, 64
	v_mov_b32_e32 v174, v59
	s_waitcnt lgkmcnt(0)
	v_mov_b32_e32 v176, v67
	s_cmp_eq_u32 s6, 0xc00000
	s_waitcnt vmcnt(14)
	v_pk_fma_f32 v[12:13], v[72:73], v[24:25], v[12:13] op_sel:[0,1,0]
	v_pk_mov_b32 v[24:25], v[72:73], v[72:73] op_sel:[1,0]
	v_mov_b32_e32 v68, v74
	v_pk_fma_f32 v[14:15], v[72:73], v[44:45], v[14:15] op_sel:[0,1,0]
	v_fmac_f32_e32 v22, v74, v45
	s_waitcnt vmcnt(13)
	v_pk_mov_b32 v[44:45], v[76:77], v[76:77] op_sel:[1,0]
	v_mov_b32_e32 v69, v25
	v_mov_b32_e32 v25, v74
	v_mov_b32_e32 v70, v78
	s_waitcnt vmcnt(12)
	v_pk_mov_b32 v[72:73], v[80:81], v[80:81] op_sel:[1,0]
	v_pk_fma_f32 v[12:13], v[76:77], v[26:27], v[12:13] op_sel_hi:[1,0,1]
	v_mov_b32_e32 v71, v45
	v_mov_b32_e32 v45, v78
	v_pk_fma_f32 v[10:11], v[68:69], v[132:133], v[10:11]
	v_pk_fma_f32 v[8:9], v[24:25], v[36:37], v[8:9] op_sel:[0,1,0]
	v_mov_b32_e32 v182, v82
	s_waitcnt vmcnt(11)
	v_pk_mov_b32 v[184:185], v[84:85], v[84:85] op_sel:[1,0]
	v_pk_fma_f32 v[14:15], v[76:77], v[46:47], v[14:15] op_sel_hi:[1,0,1]
	v_fmac_f32_e32 v22, v78, v46
	v_mov_b32_e32 v183, v73
	v_mov_b32_e32 v73, v82
	v_pk_fma_f32 v[12:13], v[80:81], v[138:139], v[12:13] op_sel_hi:[1,0,1]
	v_pk_fma_f32 v[10:11], v[70:71], v[134:135], v[10:11]
	v_pk_fma_f32 v[8:9], v[44:45], v[38:39], v[8:9] op_sel_hi:[1,0,1]
	v_mov_b32_e32 v38, v27
	v_mov_b32_e32 v186, v86
	s_waitcnt vmcnt(10)
	v_pk_mov_b32 v[188:189], v[88:89], v[88:89] op_sel:[1,0]
	v_mov_b32_e32 v187, v185
	v_mov_b32_e32 v185, v86
	v_fmac_f32_e32 v22, v82, v47
	v_pk_fma_f32 v[14:15], v[80:81], v[136:137], v[14:15] op_sel_hi:[1,0,1]
	v_pk_fma_f32 v[12:13], v[84:85], v[28:29], v[12:13] op_sel_hi:[1,0,1]
	v_pk_fma_f32 v[10:11], v[182:183], v[38:39], v[10:11]
	v_pk_fma_f32 v[8:9], v[72:73], v[140:141], v[8:9] op_sel_hi:[1,0,1]
	v_mov_b32_e32 v190, v90
	s_waitcnt vmcnt(9)
	v_pk_mov_b32 v[192:193], v[92:93], v[92:93] op_sel:[1,0]
	v_mov_b32_e32 v191, v189
	v_mov_b32_e32 v189, v90
	v_pk_fma_f32 v[14:15], v[84:85], v[48:49], v[14:15] op_sel_hi:[1,0,1]
	v_fmac_f32_e32 v22, v86, v48
	v_pk_fma_f32 v[12:13], v[88:89], v[28:29], v[12:13] op_sel:[0,1,0]
	v_pk_fma_f32 v[10:11], v[186:187], v[142:143], v[10:11]
	v_pk_fma_f32 v[8:9], v[184:185], v[40:41], v[8:9] op_sel_hi:[1,0,1]
	v_mov_b32_e32 v194, v94
	s_waitcnt vmcnt(8)
	v_pk_mov_b32 v[196:197], v[96:97], v[96:97] op_sel:[1,0]
	v_mov_b32_e32 v195, v193
	v_mov_b32_e32 v193, v94
	v_pk_fma_f32 v[14:15], v[88:89], v[48:49], v[14:15] op_sel:[0,1,0]
	v_fmac_f32_e32 v22, v90, v49
	v_pk_fma_f32 v[12:13], v[92:93], v[30:31], v[12:13] op_sel_hi:[1,0,1]
	v_pk_fma_f32 v[10:11], v[190:191], v[144:145], v[10:11]
	v_pk_fma_f32 v[8:9], v[188:189], v[40:41], v[8:9] op_sel:[0,1,0]
	v_mov_b32_e32 v198, v98
	s_waitcnt vmcnt(7)
	v_pk_mov_b32 v[200:201], v[100:101], v[100:101] op_sel:[1,0]
	v_mov_b32_e32 v199, v197
	v_mov_b32_e32 v197, v98
	v_pk_fma_f32 v[14:15], v[92:93], v[50:51], v[14:15] op_sel_hi:[1,0,1]
	v_fmac_f32_e32 v22, v94, v50
	v_pk_fma_f32 v[12:13], v[96:97], v[148:149], v[12:13] op_sel_hi:[1,0,1]
	v_pk_fma_f32 v[10:11], v[194:195], v[146:147], v[10:11]
	v_pk_fma_f32 v[8:9], v[192:193], v[42:43], v[8:9] op_sel_hi:[1,0,1]
	v_mov_b32_e32 v42, v31
	v_mov_b32_e32 v202, v102
	s_waitcnt vmcnt(6)
	v_pk_mov_b32 v[204:205], v[104:105], v[104:105] op_sel:[1,0]
	v_mov_b32_e32 v203, v201
	v_mov_b32_e32 v201, v102
	v_fmac_f32_e32 v22, v98, v51
	v_pk_fma_f32 v[14:15], v[96:97], v[152:153], v[14:15] op_sel_hi:[1,0,1]
	v_pk_fma_f32 v[12:13], v[100:101], v[32:33], v[12:13] op_sel_hi:[1,0,1]
	v_pk_fma_f32 v[10:11], v[198:199], v[42:43], v[10:11]
	v_pk_fma_f32 v[8:9], v[196:197], v[150:151], v[8:9] op_sel_hi:[1,0,1]
	v_mov_b32_e32 v206, v106
	s_waitcnt vmcnt(5)
	v_pk_mov_b32 v[208:209], v[108:109], v[108:109] op_sel:[1,0]
	v_mov_b32_e32 v207, v205
	v_mov_b32_e32 v205, v106
	v_pk_fma_f32 v[14:15], v[100:101], v[60:61], v[14:15] op_sel_hi:[1,0,1]
	v_fmac_f32_e32 v22, v102, v60
	v_pk_fma_f32 v[12:13], v[104:105], v[32:33], v[12:13] op_sel:[0,1,0]
	v_pk_fma_f32 v[10:11], v[202:203], v[154:155], v[10:11]
	v_pk_fma_f32 v[8:9], v[200:201], v[52:53], v[8:9] op_sel_hi:[1,0,1]
	v_mov_b32_e32 v210, v110
	s_waitcnt vmcnt(4)
	v_pk_mov_b32 v[212:213], v[112:113], v[112:113] op_sel:[1,0]
	v_mov_b32_e32 v211, v209
	v_mov_b32_e32 v209, v110
	v_pk_fma_f32 v[14:15], v[104:105], v[60:61], v[14:15] op_sel:[0,1,0]
	v_fmac_f32_e32 v22, v106, v61
	v_pk_fma_f32 v[12:13], v[108:109], v[34:35], v[12:13] op_sel_hi:[1,0,1]
	v_pk_fma_f32 v[10:11], v[206:207], v[156:157], v[10:11]
	v_pk_fma_f32 v[8:9], v[204:205], v[52:53], v[8:9] op_sel:[0,1,0]
	v_mov_b32_e32 v214, v114
	s_waitcnt vmcnt(3)
	v_pk_mov_b32 v[216:217], v[116:117], v[116:117] op_sel:[1,0]
	v_mov_b32_e32 v215, v213
	v_mov_b32_e32 v213, v114
	v_pk_fma_f32 v[14:15], v[108:109], v[62:63], v[14:15] op_sel_hi:[1,0,1]
	v_fmac_f32_e32 v22, v110, v62
	v_pk_fma_f32 v[12:13], v[112:113], v[160:161], v[12:13] op_sel_hi:[1,0,1]
	v_pk_fma_f32 v[10:11], v[210:211], v[158:159], v[10:11]
	v_pk_fma_f32 v[8:9], v[208:209], v[54:55], v[8:9] op_sel_hi:[1,0,1]
	v_mov_b32_e32 v54, v35
	v_mov_b32_e32 v218, v118
	s_waitcnt vmcnt(2)
	v_pk_mov_b32 v[220:221], v[120:121], v[120:121] op_sel:[1,0]
	v_mov_b32_e32 v219, v217
	v_mov_b32_e32 v217, v118
	v_fmac_f32_e32 v22, v114, v63
	v_pk_fma_f32 v[14:15], v[112:113], v[164:165], v[14:15] op_sel_hi:[1,0,1]
	v_pk_fma_f32 v[12:13], v[116:117], v[0:1], v[12:13] op_sel_hi:[1,0,1]
	v_pk_fma_f32 v[10:11], v[214:215], v[54:55], v[10:11]
	v_pk_fma_f32 v[8:9], v[212:213], v[162:163], v[8:9] op_sel_hi:[1,0,1]
	v_mov_b32_e32 v222, v122
	s_waitcnt vmcnt(1)
	v_pk_mov_b32 v[224:225], v[124:125], v[124:125] op_sel:[1,0]
	v_mov_b32_e32 v223, v221
	v_mov_b32_e32 v221, v122
	v_pk_fma_f32 v[14:15], v[116:117], v[64:65], v[14:15] op_sel_hi:[1,0,1]
	v_fmac_f32_e32 v22, v118, v64
	v_pk_fma_f32 v[0:1], v[120:121], v[0:1], v[12:13] op_sel:[0,1,0]
	v_pk_fma_f32 v[10:11], v[218:219], v[166:167], v[10:11]
	v_pk_fma_f32 v[8:9], v[216:217], v[56:57], v[8:9] op_sel_hi:[1,0,1]
	v_mov_b32_e32 v226, v126
	s_waitcnt vmcnt(0)
	v_pk_mov_b32 v[228:229], v[128:129], v[128:129] op_sel:[1,0]
	v_mov_b32_e32 v227, v225
	v_mov_b32_e32 v225, v126
	v_pk_fma_f32 v[12:13], v[120:121], v[64:65], v[14:15] op_sel:[0,1,0]
	v_fmac_f32_e32 v22, v122, v65
	v_pk_fma_f32 v[0:1], v[124:125], v[2:3], v[0:1] op_sel_hi:[1,0,1]
	v_pk_fma_f32 v[10:11], v[222:223], v[168:169], v[10:11]
	v_pk_fma_f32 v[8:9], v[220:221], v[56:57], v[8:9] op_sel:[0,1,0]
	v_mov_b32_e32 v230, v130
	v_mov_b32_e32 v231, v229
	v_mov_b32_e32 v229, v130
	v_pk_fma_f32 v[14:15], v[124:125], v[66:67], v[12:13] op_sel_hi:[1,0,1]
	v_fmac_f32_e32 v22, v126, v66
	v_pk_fma_f32 v[12:13], v[128:129], v[172:173], v[0:1] op_sel_hi:[1,0,1]
	v_pk_fma_f32 v[0:1], v[226:227], v[170:171], v[10:11]
	v_pk_fma_f32 v[8:9], v[224:225], v[58:59], v[8:9] op_sel_hi:[1,0,1]
	v_mov_b32_e32 v58, v3
	v_pk_fma_f32 v[14:15], v[128:129], v[176:177], v[14:15] op_sel_hi:[1,0,1]
	v_fmac_f32_e32 v22, v130, v67
	v_pk_fma_f32 v[10:11], v[230:231], v[58:59], v[0:1]
	v_pk_fma_f32 v[8:9], v[228:229], v[174:175], v[8:9] op_sel_hi:[1,0,1]
	s_cbranch_scc0 .LBB0_101
	ds_write2st64_b32 v19, v12, v13 offset0:96 offset1:97
	ds_write2st64_b32 v19, v10, v11 offset0:98 offset1:99
	ds_write2st64_b32 v19, v8, v9 offset0:100 offset1:101
	ds_write2st64_b32 v19, v14, v15 offset0:102 offset1:103
	ds_write_b32 v19, v22 offset:26624
	s_waitcnt lgkmcnt(0)
	s_barrier
	s_and_saveexec_b64 s[6:7], vcc
	s_cbranch_execz .LBB0_99
	v_mov_b32_e32 v0, s37
	s_and_b32 s4, s41, 63
	ds_read_b64 v[0:1], v0
	s_mulk_i32 s4, 0xc0
	s_lshl_b32 s5, s4, 2
	s_add_u32 s14, s2, s5
	s_mul_hi_i32 s42, s8, 0xc000
	s_mul_i32 s43, s8, 0xc000
	s_mul_hi_i32 s9, s8, 3
	s_mul_i32 s8, s8, 3
	s_addc_u32 s15, s18, 0
	s_mov_b64 s[16:17], 0
	s_lshl_b32 s44, s4, 2
	v_mov_b32_e32 v2, v18
